# attention prologue: first K/V tile loads issued before the Q normalisation math so both memory round trips overlap
# speedup vs baseline: 1.0030x; 1.0030x over previous
.LBB0_689:
	v_readlane_b32 s8, v254, 2
	s_add_i32 s14, s10, s8
	s_cmpk_gt_i32 s14, 0x3ff
	s_mov_b64 s[8:9], -1
	s_cbranch_scc1 .LBB0_688
	s_and_b32 s15, s14, 31
	s_bfe_u32 s8, s14, 0x10005
	v_lshl_add_u32 v0, s8, 2, v164
	s_lshl_b32 s9, s15, 6
	s_lshl_b32 s14, s14, 5
	v_or_b32_e32 v4, s9, v165
	v_ashrrev_i32_e32 v1, 31, v0
	s_and_b32 s16, s14, 0xfffff800
	v_lshl_add_u64 v[2:3], v[0:1], 2, s[6:7]
	v_or_b32_e32 v159, s16, v4
	global_load_dword v68, v[2:3], off
	v_or_b32_e32 v2, v159, v146
	v_mov_b64_e32 v[42:43], s[0:1]
	v_lshlrev_b32_e32 v160, 7, v0
	v_mad_i64_i32 v[4:5], s[24:25], v2, s97, v[42:43]
	v_ashrrev_i32_e32 v161, 31, v160
	v_lshl_add_u64 v[0:1], v[160:161], 1, v[4:5]
	v_lshl_add_u64 v[0:1], v[0:1], 0, v[32:33]
	global_load_dwordx4 v[34:37], v[0:1], off offset:2048
	global_load_dwordx4 v[38:41], v[0:1], off offset:2080
	global_load_dwordx4 v[44:47], v[0:1], off offset:2112
	global_load_dwordx4 v[48:51], v[0:1], off offset:2144
	global_load_dwordx4 v[52:55], v[0:1], off offset:2176
	global_load_dwordx4 v[56:59], v[0:1], off offset:2208
	global_load_dwordx4 v[60:63], v[0:1], off offset:2240
	global_load_dwordx4 v[64:67], v[0:1], off offset:2272
	v_ashrrev_i32_e32 v3, 31, v2
	v_lshlrev_b64 v[0:1], 7, v[2:3]
	v_lshl_add_u64 v[4:5], v[152:153], 0, v[0:1]
	global_load_dwordx4 v[0:3], v[4:5], off offset:48
	global_load_dwordx4 v[8:11], v[4:5], off offset:32
	global_load_dwordx4 v[12:15], v[4:5], off offset:16
	global_load_dwordx4 v[24:27], v[4:5], off
	global_load_dwordx4 v[16:19], v[148:149], off
	s_nop 0
	global_load_dwordx4 v[4:7], v[148:149], off offset:16
	global_load_dwordx4 v[20:23], v[148:149], off offset:64
	global_load_dwordx4 v[28:31], v[148:149], off offset:80
	s_sub_i32 s14, 2, s15
	s_cmp_lt_u32 s15, 2
	s_cselect_b32 s14, s14, 0
	s_or_b32 s9, s16, s9
	s_lshl_b32 s88, s8, 8
	v_mov_b32_e32 v157, v33
	s_mul_i32 s8, s14, 0x58000
	s_mov_b64 s[30:31], 0x1000
	s_sub_i32 s15, 33, s15
	s_min_u32 s15, s15, 4
	v_add_u32_e32 v234, s9, v167
	v_mad_i64_i32 v[234:235], s[16:17], v234, s97, v[42:43]
	v_lshl_add_u64 v[234:235], v[234:235], 0, s[88:89]
	v_lshl_add_u64 v[234:235], v[234:235], 0, v[156:157]
	s_ashr_i32 s9, s8, 31
	v_lshl_add_u64 v[236:237], s[8:9], 1, v[234:235]
	v_add_co_u32_e32 v238, vcc, s93, v236
	v_lshl_add_u64 v[234:235], v[236:237], 0, s[30:31]
	s_nop 0
	v_addc_co_u32_e32 v239, vcc, 0, v237, vcc
	v_add_co_u32_e32 v236, vcc, 0x59000, v236
	global_load_dwordx4 v[240:243], v[238:239], off
	global_load_dwordx4 v[244:247], v[234:235], off offset:512
	v_addc_co_u32_e32 v237, vcc, 0, v237, vcc
	global_load_dwordx4 v[248:251], v[236:237], off
	global_load_dwordx4 v[236:239], v[236:237], off offset:512
	s_waitcnt vmcnt(19)
	v_lshlrev_b32_e32 v93, 16, v34
	s_waitcnt vmcnt(18)
	v_lshlrev_b32_e32 v92, 16, v38
	s_waitcnt vmcnt(17)
	v_lshlrev_b32_e32 v101, 16, v46
	v_and_b32_e32 v102, 0xffff0000, v46
	s_waitcnt vmcnt(15)
	v_lshlrev_b32_e32 v113, 16, v52
	v_and_b32_e32 v114, 0xffff0000, v52
	s_waitcnt vmcnt(14)
	v_lshlrev_b32_e32 v125, 16, v58
	v_and_b32_e32 v126, 0xffff0000, v58
	v_lshlrev_b32_e32 v127, 16, v59
	v_and_b32_e32 v128, 0xffff0000, v59
	s_waitcnt vmcnt(12)
	v_and_b32_e32 v58, 0xffff0000, v67
	v_lshlrev_b32_e32 v59, 16, v67
	v_lshlrev_b32_e32 v46, 16, v41
	v_and_b32_e32 v52, 0xffff0000, v41
	v_lshlrev_b32_e32 v41, 16, v35
	v_and_b32_e32 v67, 0xffff0000, v35
	v_and_b32_e32 v35, 0xffff0000, v34
	v_and_b32_e32 v34, 0xffff0000, v38
	v_lshlrev_b32_e32 v103, 16, v47
	v_and_b32_e32 v104, 0xffff0000, v47
	v_lshlrev_b32_e32 v115, 16, v53
	v_and_b32_e32 v116, 0xffff0000, v53
	v_lshlrev_b32_e32 v121, 16, v56
	v_and_b32_e32 v122, 0xffff0000, v56
	v_lshlrev_b32_e32 v123, 16, v57
	v_and_b32_e32 v124, 0xffff0000, v57
	v_lshlrev_b32_e32 v129, 16, v60
	v_and_b32_e32 v130, 0xffff0000, v60
	v_lshlrev_b32_e32 v131, 16, v61
	v_and_b32_e32 v132, 0xffff0000, v61
	v_and_b32_e32 v56, 0xffff0000, v66
	v_lshlrev_b32_e32 v57, 16, v66
	v_lshlrev_b32_e32 v47, 16, v37
	v_and_b32_e32 v53, 0xffff0000, v37
	v_lshlrev_b32_e32 v61, 16, v36
	v_lshlrev_b32_e32 v60, 16, v40
	v_and_b32_e32 v37, 0xffff0000, v36
	v_and_b32_e32 v36, 0xffff0000, v40
	v_lshlrev_b32_e32 v40, 16, v39
	v_and_b32_e32 v66, 0xffff0000, v39
	v_pk_mul_f32 v[94:95], v[92:93], v[92:93]
	v_pk_mul_f32 v[38:39], v[34:35], v[34:35]
	v_lshlrev_b32_e32 v69, 16, v44
	v_and_b32_e32 v98, 0xffff0000, v44
	v_lshlrev_b32_e32 v99, 16, v45
	v_and_b32_e32 v100, 0xffff0000, v45
	v_and_b32_e32 v44, 0xffff0000, v63
	v_lshlrev_b32_e32 v45, 16, v63
	s_waitcnt vmcnt(6)
	v_mov_b32_e32 v63, v4
	v_pk_mul_f32 v[88:89], v[40:41], v[40:41]
	v_add_f32_e32 v4, v95, v39
	v_pk_mul_f32 v[90:91], v[66:67], v[66:67]
	v_add_f32_e32 v4, v89, v4
	v_pk_mul_f32 v[84:85], v[60:61], v[60:61]
	v_add_f32_e32 v4, v91, v4
	v_pk_mul_f32 v[86:87], v[36:37], v[36:37]
	v_add_f32_e32 v4, v85, v4
	v_pk_mul_f32 v[80:81], v[46:47], v[46:47]
	v_add_f32_e32 v4, v87, v4
	v_pk_mul_f32 v[82:83], v[52:53], v[52:53]
	v_add_f32_e32 v4, v81, v4
	v_add_f32_e32 v4, v83, v4
	v_add_f32_e32 v4, v94, v4
	v_add_f32_e32 v4, v38, v4
	v_add_f32_e32 v4, v88, v4
	v_add_f32_e32 v4, v90, v4
	v_add_f32_e32 v4, v84, v4
	v_add_f32_e32 v4, v86, v4
	v_add_f32_e32 v4, v80, v4
	v_add_f32_e32 v4, v82, v4
	v_fmac_f32_e32 v4, v69, v69
	v_fmac_f32_e32 v4, v98, v98
	v_fmac_f32_e32 v4, v99, v99
	v_fmac_f32_e32 v4, v100, v100
	v_fmac_f32_e32 v4, v101, v101
	v_fmac_f32_e32 v4, v102, v102
	v_fmac_f32_e32 v4, v103, v103
	v_lshlrev_b32_e32 v105, 16, v48
	v_fmac_f32_e32 v4, v104, v104
	v_and_b32_e32 v106, 0xffff0000, v48
	v_fmac_f32_e32 v4, v105, v105
	v_lshlrev_b32_e32 v107, 16, v49
	v_fmac_f32_e32 v4, v106, v106
	v_and_b32_e32 v108, 0xffff0000, v49
	v_fmac_f32_e32 v4, v107, v107
	v_lshlrev_b32_e32 v109, 16, v50
	v_fmac_f32_e32 v4, v108, v108
	v_and_b32_e32 v110, 0xffff0000, v50
	v_fmac_f32_e32 v4, v109, v109
	v_lshlrev_b32_e32 v111, 16, v51
	v_fmac_f32_e32 v4, v110, v110
	v_and_b32_e32 v112, 0xffff0000, v51
	v_fmac_f32_e32 v4, v111, v111
	v_fmac_f32_e32 v4, v112, v112
	v_fmac_f32_e32 v4, v113, v113
	v_fmac_f32_e32 v4, v114, v114
	v_fmac_f32_e32 v4, v115, v115
	v_lshlrev_b32_e32 v117, 16, v54
	v_fmac_f32_e32 v4, v116, v116
	v_and_b32_e32 v118, 0xffff0000, v54
	v_fmac_f32_e32 v4, v117, v117
	v_lshlrev_b32_e32 v119, 16, v55
	v_fmac_f32_e32 v4, v118, v118
	v_and_b32_e32 v120, 0xffff0000, v55
	v_fmac_f32_e32 v4, v119, v119
	v_fmac_f32_e32 v4, v120, v120
	v_fmac_f32_e32 v4, v121, v121
	v_fmac_f32_e32 v4, v122, v122
	v_fmac_f32_e32 v4, v123, v123
	v_fmac_f32_e32 v4, v124, v124
	v_fmac_f32_e32 v4, v125, v125
	v_fmac_f32_e32 v4, v126, v126
	v_fmac_f32_e32 v4, v127, v127
	v_fmac_f32_e32 v4, v128, v128
	v_fmac_f32_e32 v4, v129, v129
	v_fmac_f32_e32 v4, v130, v130
	v_fmac_f32_e32 v4, v131, v131
	v_lshlrev_b32_e32 v133, 16, v62
	v_fmac_f32_e32 v4, v132, v132
	v_and_b32_e32 v134, 0xffff0000, v62
	v_fmac_f32_e32 v4, v133, v133
	v_pk_mul_f32 v[70:71], v[44:45], v[44:45]
	v_fmac_f32_e32 v4, v134, v134
	v_and_b32_e32 v48, 0xffff0000, v64
	v_lshlrev_b32_e32 v49, 16, v64
	v_add_f32_e32 v4, v71, v4
	v_pk_mul_f32 v[72:73], v[48:49], v[48:49]
	v_add_f32_e32 v4, v70, v4
	v_and_b32_e32 v54, 0xffff0000, v65
	v_lshlrev_b32_e32 v55, 16, v65
	v_add_f32_e32 v4, v73, v4
	v_pk_mul_f32 v[74:75], v[54:55], v[54:55]
	v_add_f32_e32 v4, v72, v4
	v_add_f32_e32 v4, v75, v4
	v_pk_mul_f32 v[76:77], v[56:57], v[56:57]
	v_add_f32_e32 v4, v74, v4
	v_add_f32_e32 v4, v77, v4
	v_pk_mul_f32 v[78:79], v[58:59], v[58:59]
	v_add_f32_e32 v4, v76, v4
	v_add_f32_e32 v4, v79, v4
	v_add_f32_e32 v4, v78, v4
	v_mov_b32_e32 v51, v6
	ds_bpermute_b32 v6, v147, v4
	s_waitcnt vmcnt(4)
	v_mov_b32_e32 v50, v30
	v_mov_b32_e32 v64, v22
	v_mov_b32_e32 v97, v16
	v_mov_b32_e32 v62, v28
	s_waitcnt lgkmcnt(0)
	v_add_f32_e32 v4, v4, v6
	v_fmamk_f32 v4, v4, 0x3c000000, v218
	v_cmp_gt_f32_e32 vcc, s18, v4
	v_mul_f32_e32 v6, 0x4b800000, v4
	v_mov_b32_e32 v96, v20
	v_cndmask_b32_e32 v4, v4, v6, vcc
	v_rsq_f32_e32 v4, v4
	v_mov_b32_e32 v65, v18
	v_mul_f32_e32 v6, 0x45800000, v4
	v_cndmask_b32_e32 v4, v4, v6, vcc
	v_mul_f32_e32 v6, 0x3e0293ee, v4
	v_mul_f32_e32 v38, v6, v104
	v_mul_f32_e32 v4, v6, v69
	v_mul_f32_e32 v22, v6, v101
	v_mul_f32_e32 v30, v6, v103
	v_cvt_pk_bf16_f32 v101, v30, v38
	v_mul_f32_e32 v38, v6, v112
	v_mul_f32_e32 v16, v6, v98
	v_cvt_pk_bf16_f32 v98, v4, v16
	v_mul_f32_e32 v4, v6, v105
	v_mul_f32_e32 v30, v6, v111
	v_cvt_pk_bf16_f32 v105, v30, v38
	v_mul_f32_e32 v38, v6, v120
	v_mul_f32_e32 v20, v6, v100
	v_mul_f32_e32 v28, v6, v102
	v_cvt_pk_bf16_f32 v100, v22, v28
	v_mul_f32_e32 v22, v6, v109
	v_mul_f32_e32 v30, v6, v119
	v_cvt_pk_bf16_f32 v109, v30, v38
	v_mul_f32_e32 v38, v6, v128
	v_mul_f32_e32 v16, v6, v106
	v_mul_f32_e32 v28, v6, v110
	v_cvt_pk_bf16_f32 v102, v4, v16
	v_mul_f32_e32 v4, v6, v113
	v_mul_f32_e32 v30, v6, v127
	v_cvt_pk_bf16_f32 v113, v30, v38
	v_mul_f32_e32 v38, v6, v44
	v_cvt_pk_bf16_f32 v104, v22, v28
	v_mul_f32_e32 v16, v6, v114
	v_mul_f32_e32 v22, v6, v117
	v_mul_f32_e32 v28, v6, v118
	v_mul_f32_e32 v30, v6, v45
	v_cvt_pk_bf16_f32 v117, v30, v38
	v_mul_f32_e32 v38, v6, v58
	v_mul_f32_e32 v18, v6, v99
	v_cvt_pk_bf16_f32 v99, v18, v20
	v_mul_f32_e32 v20, v6, v108
	v_cvt_pk_bf16_f32 v106, v4, v16
	v_cvt_pk_bf16_f32 v108, v22, v28
	v_mul_f32_e32 v4, v6, v121
	v_mul_f32_e32 v16, v6, v122
	v_mul_f32_e32 v28, v6, v126
	v_mul_f32_e32 v30, v6, v59
	v_cvt_pk_bf16_f32 v121, v30, v38
	v_pk_mul_f32 v[38:39], v[6:7], v[92:93] op_sel_hi:[0,1]
	v_mul_f32_e32 v18, v6, v107
	v_cvt_pk_bf16_f32 v103, v18, v20
	v_mul_f32_e32 v20, v6, v116
	v_mul_f32_e32 v22, v6, v125
	v_cvt_pk_bf16_f32 v110, v4, v16
	v_cvt_pk_bf16_f32 v112, v22, v28
	v_mul_f32_e32 v16, v6, v130
	v_mul_f32_e32 v28, v6, v134
	v_pk_mul_f32 v[38:39], v[96:97], v[38:39]
	v_mul_f32_e32 v18, v6, v115
	v_cvt_pk_bf16_f32 v107, v18, v20
	v_mul_f32_e32 v20, v6, v124
	v_mul_f32_e32 v4, v6, v129
	v_mul_f32_e32 v22, v6, v133
	v_cvt_pk_bf16_f32 v114, v4, v16
	v_cvt_pk_bf16_f32 v116, v22, v28
	v_mul_f32_e32 v16, v6, v48
	v_mul_f32_e32 v28, v6, v56
	v_pk_mul_f32 v[44:45], v[24:25], v[38:39] op_sel:[0,1] op_sel_hi:[1,0]
	v_pk_mul_f32 v[24:25], v[24:25], v[38:39]
	v_mul_f32_e32 v18, v6, v123
	v_cvt_pk_bf16_f32 v111, v18, v20
	v_mul_f32_e32 v20, v6, v132
	v_mul_f32_e32 v4, v6, v49
	v_mul_f32_e32 v22, v6, v57
	v_cvt_pk_bf16_f32 v118, v4, v16
	v_cvt_pk_bf16_f32 v120, v22, v28
	v_add_f32_e32 v28, v24, v25
	v_pk_mul_f32 v[24:25], v[6:7], v[34:35] op_sel_hi:[0,1]
	v_mov_b32_e32 v16, v21
	v_mul_f32_e32 v18, v6, v131
	v_cvt_pk_bf16_f32 v115, v18, v20
	v_mul_f32_e32 v20, v6, v54
	v_pk_mul_f32 v[16:17], v[16:17], v[24:25]
	v_mul_f32_e32 v18, v6, v55
	v_cvt_pk_bf16_f32 v119, v18, v20
	v_pk_mul_f32 v[20:21], v[26:27], v[16:17] op_sel:[0,1] op_sel_hi:[1,0]
	v_pk_mul_f32 v[16:17], v[26:27], v[16:17]
	v_sub_f32_e32 v24, v20, v21
	v_add_f32_e32 v25, v16, v17
	v_pk_mul_f32 v[16:17], v[6:7], v[40:41] op_sel_hi:[0,1]
	v_pk_mul_f32 v[16:17], v[64:65], v[16:17]
	v_mov_b32_e32 v18, v23
	v_pk_mul_f32 v[20:21], v[12:13], v[16:17] op_sel:[0,1] op_sel_hi:[1,0]
	v_pk_mul_f32 v[12:13], v[12:13], v[16:17]
	v_sub_f32_e32 v20, v20, v21
	v_add_f32_e32 v21, v12, v13
	v_pk_mul_f32 v[12:13], v[6:7], v[66:67] op_sel_hi:[0,1]
	v_pk_mul_f32 v[12:13], v[18:19], v[12:13]
	v_mov_b32_e32 v4, v29
	v_pk_mul_f32 v[16:17], v[14:15], v[12:13] op_sel:[0,1] op_sel_hi:[1,0]
	v_pk_mul_f32 v[12:13], v[14:15], v[12:13]
	v_sub_f32_e32 v16, v16, v17
	v_add_f32_e32 v17, v12, v13
	v_pk_mul_f32 v[12:13], v[6:7], v[60:61] op_sel_hi:[0,1]
	v_pk_mul_f32 v[12:13], v[62:63], v[12:13]
	v_sub_f32_e32 v22, v44, v45
	v_pk_mul_f32 v[14:15], v[8:9], v[12:13] op_sel:[0,1] op_sel_hi:[1,0]
	v_pk_mul_f32 v[8:9], v[8:9], v[12:13]
	v_sub_f32_e32 v14, v14, v15
	v_add_f32_e32 v12, v8, v9
	v_pk_mul_f32 v[8:9], v[6:7], v[36:37] op_sel_hi:[0,1]
	v_pk_mul_f32 v[4:5], v[4:5], v[8:9]
	v_cvt_pk_bf16_f32 v122, v22, v24
	v_cvt_pk_bf16_f32 v123, v20, v16
	v_cvt_pk_bf16_f32 v126, v28, v25
	v_cvt_pk_bf16_f32 v127, v21, v17
	s_nop 0
	v_pk_mul_f32 v[8:9], v[10:11], v[4:5] op_sel:[0,1] op_sel_hi:[1,0]
	v_pk_mul_f32 v[4:5], v[10:11], v[4:5]
	v_sub_f32_e32 v13, v8, v9
	v_add_f32_e32 v10, v4, v5
	v_pk_mul_f32 v[4:5], v[6:7], v[46:47] op_sel_hi:[0,1]
	v_pk_mul_f32 v[4:5], v[50:51], v[4:5]
	v_cvt_pk_bf16_f32 v124, v14, v13
	v_cvt_pk_bf16_f32 v128, v12, v10
	s_nop 0
	v_pk_mul_f32 v[8:9], v[0:1], v[4:5] op_sel:[0,1] op_sel_hi:[1,0]
	v_pk_mul_f32 v[0:1], v[0:1], v[4:5]
	v_sub_f32_e32 v8, v8, v9
	v_add_f32_e32 v9, v0, v1
	v_pk_mul_f32 v[0:1], v[6:7], v[52:53] op_sel_hi:[0,1]
	v_mov_b32_e32 v6, v31
	v_pk_mul_f32 v[0:1], v[6:7], v[0:1]
	s_nop 0
	v_pk_mul_f32 v[4:5], v[2:3], v[0:1] op_sel:[0,1] op_sel_hi:[1,0]
	v_pk_mul_f32 v[0:1], v[2:3], v[0:1]
	v_sub_f32_e32 v4, v4, v5
	v_add_f32_e32 v0, v0, v1
	v_cvt_pk_bf16_f32 v129, v9, v0
	v_cvt_pk_bf16_f32 v125, v8, v4
	s_cmp_ge_i32 s14, s15
	s_waitcnt vmcnt(3)
	ds_write_b128 v171, v[240:243]
	s_waitcnt vmcnt(2)
	ds_write_b128 v171, v[244:247] offset:17408
	s_waitcnt vmcnt(1)
	ds_write_b128 v171, v[248:251] offset:8704
	s_waitcnt vmcnt(0)
	ds_write_b128 v171, v[236:239] offset:26112
	s_cbranch_scc1 .LBB0_692
	s_mov_b64 s[8:9], 0x200
	v_add_co_u32_e32 v4, vcc, 0xb0000, v234
	v_lshl_add_u64 v[2:3], v[234:235], 0, s[8:9]
	s_nop 0
	v_addc_co_u32_e32 v5, vcc, 0, v235, vcc
	v_add_co_u32_e32 v6, vcc, 0xb0000, v2
	s_nop 1
	v_addc_co_u32_e32 v7, vcc, 0, v3, vcc
	v_add_co_u32_e32 v0, vcc, 0x108000, v234
	global_load_dwordx4 v[130:133], v[4:5], off
	global_load_dwordx4 v[134:137], v[6:7], off
	v_addc_co_u32_e32 v1, vcc, 0, v235, vcc
	v_add_co_u32_e32 v2, vcc, 0x108000, v2
	s_nop 1
	v_addc_co_u32_e32 v3, vcc, 0, v3, vcc
	global_load_dwordx4 v[138:141], v[0:1], off
	global_load_dwordx4 v[142:145], v[2:3], off
